# attention: local QK K-loads 14-deep ring + branch-free bias (LDS reads pipelined, cndmask)
# speedup vs baseline: 1.0123x; 1.0123x over previous
; __device__ __forceinline__ void attn_phase(const Params& p, const bf16_t* qk, const bf16_t* vT, bf16_t* ob, char* smem) {
;     ...
;             int r = 0, c0 = 0, qtok0;
;             if (!isctx) { r = half * 32 + (ul >> 2); c0 = (ul & 3) * 16; qtok0 = b * 4096 + r * 64 + c0; }
;             else { qtok0 = T_LAT + b * 256 + (half * 8 + (ul - 128)) * 16; }
;             bf16x8 qf[2];
; #pragma unroll
;             for (int ks = 0; ks < 2; ++ks) qf[ks] = ld8(qk + (size_t)(qtok0 + fr) * 2048 + h * 64 + ks * 32 + fq * 8);
;             const bf16_t* vrow = vT + (size_t)(h * 64 + fr) * T_ALL;
;             float mL = NEG, lL = 0.f;
;             f32x4 oL[4];
; #pragma unroll
;             for (int dt = 0; dt < 4; ++dt) oL[dt] = (f32x4){0.f, 0.f, 0.f, 0.f};
;             if (!isctx) {
;                 f32x4 s[16];
;                 const int rs = min(max(r - 4, 0), 56), cst = min(max(c0 - 8, 0), 32);
; #pragma unroll
;                 for (int i = 0; i < 8; ++i)
; #pragma unroll
;                     for (int ts = 0; ts < 2; ++ts) {
;                         const size_t kt = (size_t)(b * 4096 + (rs + i) * 64 + cst + kro + ts * 4) * 2048 + 1024 + h * 64 + fq * 8;
;                         f32x4 z = {0.f, 0.f, 0.f, 0.f};
;                         z = mfma16(ld8(qk + kt), qf[0], z);
;                         z = mfma16(ld8(qk + kt + 32), qf[1], z);
;                         s[i * 2 + ts] = z;
;                     }
.LBB0_262:
	v_add_u32_e32 v100, s4, v104
	v_ashrrev_i32_e32 v101, 31, v100
	v_lshlrev_b64 v[2:3], 12, v[100:101]
	v_lshl_add_u64 v[2:3], v[94:95], 0, v[2:3]
	global_load_dwordx4 v[6:9], v[2:3], off
	s_nop 0
	global_load_dwordx4 v[2:5], v[2:3], off offset:64
	s_mov_b64 s[10:11], -1
	s_and_b64 vcc, exec, s[12:13]
	s_cbranch_vccz .LBB0_392
	s_max_i32 s0, s14, 4
	s_add_i32 s0, s0, -4
	v_sub_u32_e64 v10, s15, 8 clamp
	s_min_u32 s10, s0, 56
	v_readfirstlane_b32 s0, v10
	s_min_u32 s4, s0, 32
	s_lshl_b32 s7, s10, 6
	s_or_b32 s0, s7, s4
	v_add_u32_e32 v10, s0, v109
	v_or_b32_e32 v83, s15, v104
	s_sub_i32 s0, s10, s14
	v_add_u32_e32 v102, s4, v86
	s_mulk_i32 s0, 0x7c
	s_add_i32 s18, s79, s0
	v_mov_b32_e32 v248, v10
	v_ashrrev_i32_e32 v249, 31, v248
	v_lshlrev_b64 v[248:249], 12, v[248:249]
	v_lshl_add_u64 v[248:249], v[94:95], 0, v[248:249]
	global_load_dwordx4 v[192:195], v[248:249], off offset:2048
	global_load_dwordx4 v[196:199], v[248:249], off offset:2112
	v_add_u32_e32 v248, 0x4, v10
	v_ashrrev_i32_e32 v249, 31, v248
	v_lshlrev_b64 v[248:249], 12, v[248:249]
	v_lshl_add_u64 v[248:249], v[94:95], 0, v[248:249]
	global_load_dwordx4 v[200:203], v[248:249], off offset:2048
	global_load_dwordx4 v[204:207], v[248:249], off offset:2112
	v_add_u32_e32 v248, 0x40, v10
	v_ashrrev_i32_e32 v249, 31, v248
	v_lshlrev_b64 v[248:249], 12, v[248:249]
	v_lshl_add_u64 v[248:249], v[94:95], 0, v[248:249]
	global_load_dwordx4 v[208:211], v[248:249], off offset:2048
	global_load_dwordx4 v[212:215], v[248:249], off offset:2112
	v_add_u32_e32 v248, 0x44, v10
	v_ashrrev_i32_e32 v249, 31, v248
	v_lshlrev_b64 v[248:249], 12, v[248:249]
	v_lshl_add_u64 v[248:249], v[94:95], 0, v[248:249]
	global_load_dwordx4 v[216:219], v[248:249], off offset:2048
	global_load_dwordx4 v[220:223], v[248:249], off offset:2112
	v_add_u32_e32 v248, 0x80, v10
	v_ashrrev_i32_e32 v249, 31, v248
	v_lshlrev_b64 v[248:249], 12, v[248:249]
	v_lshl_add_u64 v[248:249], v[94:95], 0, v[248:249]
	global_load_dwordx4 v[224:227], v[248:249], off offset:2048
	global_load_dwordx4 v[228:231], v[248:249], off offset:2112
	v_add_u32_e32 v248, 0x84, v10
	v_ashrrev_i32_e32 v249, 31, v248
	v_lshlrev_b64 v[248:249], 12, v[248:249]
	v_lshl_add_u64 v[248:249], v[94:95], 0, v[248:249]
	global_load_dwordx4 v[232:235], v[248:249], off offset:2048
	global_load_dwordx4 v[236:239], v[248:249], off offset:2112
	v_add_u32_e32 v248, 0xc0, v10
	v_ashrrev_i32_e32 v249, 31, v248
	v_lshlrev_b64 v[248:249], 12, v[248:249]
	v_lshl_add_u64 v[248:249], v[94:95], 0, v[248:249]
	global_load_dwordx4 v[240:243], v[248:249], off offset:2048
	global_load_dwordx4 v[244:247], v[248:249], off offset:2112
	s_waitcnt vmcnt(13)
	v_mfma_f32_16x16x32_bf16 v[70:73], v[192:195], v[6:9], 0
	v_add_u32_e32 v248, 0xc4, v10
	v_ashrrev_i32_e32 v249, 31, v248
	v_lshlrev_b64 v[248:249], 12, v[248:249]
	v_lshl_add_u64 v[248:249], v[94:95], 0, v[248:249]
	global_load_dwordx4 v[192:195], v[248:249], off offset:2048
	s_waitcnt vmcnt(13)
	v_mfma_f32_16x16x32_bf16 v[70:73], v[196:199], v[2:5], v[70:73]
	global_load_dwordx4 v[196:199], v[248:249], off offset:2112
	s_waitcnt vmcnt(13)
	v_mfma_f32_16x16x32_bf16 v[66:69], v[200:203], v[6:9], 0
	v_add_u32_e32 v248, 0x100, v10
	v_ashrrev_i32_e32 v249, 31, v248
	v_lshlrev_b64 v[248:249], 12, v[248:249]
	v_lshl_add_u64 v[248:249], v[94:95], 0, v[248:249]
	global_load_dwordx4 v[200:203], v[248:249], off offset:2048
	s_waitcnt vmcnt(13)
	v_mfma_f32_16x16x32_bf16 v[66:69], v[204:207], v[2:5], v[66:69]
	global_load_dwordx4 v[204:207], v[248:249], off offset:2112
	s_waitcnt vmcnt(13)
	v_mfma_f32_16x16x32_bf16 v[62:65], v[208:211], v[6:9], 0
	v_add_u32_e32 v248, 0x104, v10
	v_ashrrev_i32_e32 v249, 31, v248
	v_lshlrev_b64 v[248:249], 12, v[248:249]
	v_lshl_add_u64 v[248:249], v[94:95], 0, v[248:249]
	global_load_dwordx4 v[208:211], v[248:249], off offset:2048
	s_waitcnt vmcnt(13)
	v_mfma_f32_16x16x32_bf16 v[62:65], v[212:215], v[2:5], v[62:65]
	global_load_dwordx4 v[212:215], v[248:249], off offset:2112
	s_waitcnt vmcnt(13)
	v_mfma_f32_16x16x32_bf16 v[58:61], v[216:219], v[6:9], 0
	v_add_u32_e32 v248, 0x140, v10
	v_ashrrev_i32_e32 v249, 31, v248
	v_lshlrev_b64 v[248:249], 12, v[248:249]
	v_lshl_add_u64 v[248:249], v[94:95], 0, v[248:249]
	global_load_dwordx4 v[216:219], v[248:249], off offset:2048
	s_waitcnt vmcnt(13)
	v_mfma_f32_16x16x32_bf16 v[58:61], v[220:223], v[2:5], v[58:61]
	global_load_dwordx4 v[220:223], v[248:249], off offset:2112
	s_waitcnt vmcnt(13)
	v_mfma_f32_16x16x32_bf16 v[54:57], v[224:227], v[6:9], 0
	v_add_u32_e32 v248, 0x144, v10
	v_ashrrev_i32_e32 v249, 31, v248
	v_lshlrev_b64 v[248:249], 12, v[248:249]
	v_lshl_add_u64 v[248:249], v[94:95], 0, v[248:249]
	global_load_dwordx4 v[224:227], v[248:249], off offset:2048
	s_waitcnt vmcnt(13)
	v_mfma_f32_16x16x32_bf16 v[54:57], v[228:231], v[2:5], v[54:57]
	global_load_dwordx4 v[228:231], v[248:249], off offset:2112
	s_waitcnt vmcnt(13)
	v_mfma_f32_16x16x32_bf16 v[50:53], v[232:235], v[6:9], 0
	v_add_u32_e32 v248, 0x180, v10
	v_ashrrev_i32_e32 v249, 31, v248
	v_lshlrev_b64 v[248:249], 12, v[248:249]
	v_lshl_add_u64 v[248:249], v[94:95], 0, v[248:249]
	global_load_dwordx4 v[232:235], v[248:249], off offset:2048
	s_waitcnt vmcnt(13)
	v_mfma_f32_16x16x32_bf16 v[50:53], v[236:239], v[2:5], v[50:53]
	global_load_dwordx4 v[236:239], v[248:249], off offset:2112
	s_waitcnt vmcnt(13)
	v_mfma_f32_16x16x32_bf16 v[46:49], v[240:243], v[6:9], 0
	v_add_u32_e32 v248, 0x184, v10
	v_ashrrev_i32_e32 v249, 31, v248
	v_lshlrev_b64 v[248:249], 12, v[248:249]
	v_lshl_add_u64 v[248:249], v[94:95], 0, v[248:249]
	global_load_dwordx4 v[240:243], v[248:249], off offset:2048
	s_waitcnt vmcnt(13)
; __device__ __forceinline__ void attn_phase(const Params& p, const bf16_t* qk, const bf16_t* vT, bf16_t* ob, char* smem) {
;     ...
;                 for (int i = 0; i < 8; ++i)
; #pragma unroll
;                     for (int ts = 0; ts < 2; ++ts) {
;                         const size_t kt = (size_t)(b * 4096 + (rs + i) * 64 + cst + kro + ts * 4) * 2048 + 1024 + h * 64 + fq * 8;
;                         f32x4 z = {0.f, 0.f, 0.f, 0.f};
;                         z = mfma16(ld8(qk + kt), qf[0], z);
;                         z = mfma16(ld8(qk + kt + 32), qf[1], z);
;                         s[i * 2 + ts] = z;
;                     }
;                 const int cq = c0 + fr, cs = min(max(cq - 8, 0), 48);
;                 const float* sbh = sb + h * 465 + (rs - r + 7) * 31;
; #pragma unroll
;                 for (int i = 0; i < 8; ++i)
; #pragma unroll
;                     for (int ts = 0; ts < 2; ++ts)
; #pragma unroll
;                         for (int j = 0; j < 4; ++j) {
;                             const int kc = cst + fq * 8 + ts * 4 + j;
;                             const bool valid = (kc >= cs) && (kc < cs + 16);
;                             const int ci = min(max(kc - cq + 15, 0), 30);
;                             const float bias = sbh[i * 31 + ci];
;                             s[i * 2 + ts][j] = valid ? s[i * 2 + ts][j] + bias : NEG;
;                         }
	v_mfma_f32_16x16x32_bf16 v[46:49], v[244:247], v[2:5], v[46:49]
	global_load_dwordx4 v[244:247], v[248:249], off offset:2112
	s_waitcnt vmcnt(13)
	v_mfma_f32_16x16x32_bf16 v[42:45], v[192:195], v[6:9], 0
	v_add_u32_e32 v248, 0x1c0, v10
	v_ashrrev_i32_e32 v249, 31, v248
	v_lshlrev_b64 v[248:249], 12, v[248:249]
	v_lshl_add_u64 v[248:249], v[94:95], 0, v[248:249]
	global_load_dwordx4 v[192:195], v[248:249], off offset:2048
	s_waitcnt vmcnt(13)
	v_mfma_f32_16x16x32_bf16 v[42:45], v[196:199], v[2:5], v[42:45]
	global_load_dwordx4 v[196:199], v[248:249], off offset:2112
	s_waitcnt vmcnt(13)
	v_mfma_f32_16x16x32_bf16 v[30:33], v[200:203], v[6:9], 0
	v_add_u32_e32 v248, 0x1c4, v10
	v_ashrrev_i32_e32 v249, 31, v248
	v_lshlrev_b64 v[248:249], 12, v[248:249]
	v_lshl_add_u64 v[248:249], v[94:95], 0, v[248:249]
	global_load_dwordx4 v[200:203], v[248:249], off offset:2048
	s_waitcnt vmcnt(13)
	v_mfma_f32_16x16x32_bf16 v[30:33], v[204:207], v[2:5], v[30:33]
	global_load_dwordx4 v[204:207], v[248:249], off offset:2112
	s_waitcnt vmcnt(13)
	v_mfma_f32_16x16x32_bf16 v[26:29], v[208:211], v[6:9], 0
	s_waitcnt vmcnt(12)
	v_mfma_f32_16x16x32_bf16 v[26:29], v[212:215], v[2:5], v[26:29]
	s_waitcnt vmcnt(11)
	v_mfma_f32_16x16x32_bf16 v[38:41], v[216:219], v[6:9], 0
	s_waitcnt vmcnt(10)
	v_mfma_f32_16x16x32_bf16 v[38:41], v[220:223], v[2:5], v[38:41]
	s_waitcnt vmcnt(9)
	v_mfma_f32_16x16x32_bf16 v[34:37], v[224:227], v[6:9], 0
	s_waitcnt vmcnt(8)
	v_mfma_f32_16x16x32_bf16 v[34:37], v[228:231], v[2:5], v[34:37]
	s_waitcnt vmcnt(7)
	v_mfma_f32_16x16x32_bf16 v[22:25], v[232:235], v[6:9], 0
	s_waitcnt vmcnt(6)
	v_mfma_f32_16x16x32_bf16 v[22:25], v[236:239], v[2:5], v[22:25]
	s_waitcnt vmcnt(5)
	v_mfma_f32_16x16x32_bf16 v[18:21], v[240:243], v[6:9], 0
	s_waitcnt vmcnt(4)
	v_mfma_f32_16x16x32_bf16 v[18:21], v[244:247], v[2:5], v[18:21]
	s_waitcnt vmcnt(3)
	v_mfma_f32_16x16x32_bf16 v[14:17], v[192:195], v[6:9], 0
	s_waitcnt vmcnt(2)
	v_mfma_f32_16x16x32_bf16 v[14:17], v[196:199], v[2:5], v[14:17]
	s_waitcnt vmcnt(1)
	v_mfma_f32_16x16x32_bf16 v[10:13], v[200:203], v[6:9], 0
	s_waitcnt vmcnt(0)
	v_mfma_f32_16x16x32_bf16 v[10:13], v[204:207], v[2:5], v[10:13]
	v_max_i32_e32 v216, 8, v83
	v_add_u32_e32 v216, -8, v216
	v_min_u32_e32 v217, 48, v216
	v_add_u32_e32 v218, 16, v217
	v_mov_b32_e32 v215, 0xf149f2ca
	v_cmp_ge_u32_e32 vcc, v102, v217
	v_cmp_lt_u32_e64 s[44:45], v102, v218
	v_sub_u32_e32 v219, v102, v83
	s_and_b64 s[10:11], vcc, s[44:45]
	v_max_i32_e32 v219, -15, v219
	v_add_u32_e32 v219, 15, v219
	v_min_u32_e32 v219, 30, v219
	v_lshl_add_u32 v236, v219, 2, s18
	v_or_b32_e32 v219, 1, v102
	v_cmp_ge_u32_e32 vcc, v219, v217
	v_cmp_lt_u32_e64 s[44:45], v219, v218
	v_sub_u32_e32 v219, v219, v83
	s_and_b64 s[12:13], vcc, s[44:45]
	v_max_i32_e32 v219, -15, v219
	v_add_u32_e32 v219, 15, v219
	v_min_u32_e32 v219, 30, v219
	v_lshl_add_u32 v237, v219, 2, s18
	v_or_b32_e32 v219, 2, v102
	v_cmp_ge_u32_e32 vcc, v219, v217
	v_cmp_lt_u32_e64 s[44:45], v219, v218
	v_sub_u32_e32 v219, v219, v83
	s_and_b64 s[14:15], vcc, s[44:45]
	v_max_i32_e32 v219, -15, v219
	v_add_u32_e32 v219, 15, v219
	v_min_u32_e32 v219, 30, v219
	v_lshl_add_u32 v238, v219, 2, s18
	v_or_b32_e32 v219, 3, v102
	v_cmp_ge_u32_e32 vcc, v219, v217
	v_cmp_lt_u32_e64 s[44:45], v219, v218
	v_sub_u32_e32 v219, v219, v83
	s_and_b64 s[16:17], vcc, s[44:45]
	v_max_i32_e32 v219, -15, v219
	v_add_u32_e32 v219, 15, v219
	v_min_u32_e32 v219, 30, v219
	v_lshl_add_u32 v239, v219, 2, s18
	v_or_b32_e32 v219, 4, v102
	v_cmp_ge_u32_e32 vcc, v219, v217
	v_cmp_lt_u32_e64 s[44:45], v219, v218
	v_sub_u32_e32 v219, v219, v83
	s_and_b64 s[40:41], vcc, s[44:45]
	v_max_i32_e32 v219, -15, v219
	v_add_u32_e32 v219, 15, v219
	v_min_u32_e32 v219, 30, v219
	v_lshl_add_u32 v240, v219, 2, s18
	v_or_b32_e32 v219, 5, v102
	v_cmp_ge_u32_e32 vcc, v219, v217
	v_cmp_lt_u32_e64 s[44:45], v219, v218
	v_sub_u32_e32 v219, v219, v83
	s_and_b64 s[62:63], vcc, s[44:45]
	v_max_i32_e32 v219, -15, v219
	v_add_u32_e32 v219, 15, v219
	v_min_u32_e32 v219, 30, v219
	v_lshl_add_u32 v241, v219, 2, s18
	v_or_b32_e32 v219, 6, v102
	v_cmp_ge_u32_e32 vcc, v219, v217
	v_cmp_lt_u32_e64 s[44:45], v219, v218
	v_sub_u32_e32 v219, v219, v83
	s_and_b64 s[64:65], vcc, s[44:45]
	v_max_i32_e32 v219, -15, v219
	v_add_u32_e32 v219, 15, v219
	v_min_u32_e32 v219, 30, v219
	v_lshl_add_u32 v242, v219, 2, s18
	v_or_b32_e32 v219, 7, v102
	v_cmp_ge_u32_e32 vcc, v219, v217
	v_cmp_lt_u32_e64 s[44:45], v219, v218
	v_sub_u32_e32 v219, v219, v83
	s_and_b64 s[66:67], vcc, s[44:45]
	v_max_i32_e32 v219, -15, v219
	v_add_u32_e32 v219, 15, v219
	v_min_u32_e32 v219, 30, v219
	v_lshl_add_u32 v243, v219, 2, s18
	ds_read_b32 v220, v236 offset:868
	ds_read_b32 v221, v237 offset:868
	ds_read_b32 v222, v238 offset:868
	ds_read_b32 v223, v239 offset:868
	ds_read_b32 v224, v240 offset:868
	ds_read_b32 v225, v241 offset:868
	ds_read_b32 v226, v242 offset:868
	ds_read_b32 v227, v243 offset:868
	ds_read_b32 v228, v236 offset:992
	ds_read_b32 v229, v237 offset:992
	ds_read_b32 v230, v238 offset:992
	ds_read_b32 v231, v239 offset:992
	s_waitcnt lgkmcnt(11)
	v_add_f32_e32 v220, v70, v220
	v_cndmask_b32_e64 v75, v215, v220, s[10:11]
	ds_read_b32 v220, v240 offset:992
	s_waitcnt lgkmcnt(11)
	v_add_f32_e32 v221, v71, v221
	v_cndmask_b32_e64 v74, v215, v221, s[12:13]
	ds_read_b32 v221, v241 offset:992
	s_waitcnt lgkmcnt(11)
	v_add_f32_e32 v222, v72, v222
	v_cndmask_b32_e64 v71, v215, v222, s[14:15]
	ds_read_b32 v222, v242 offset:992
	s_waitcnt lgkmcnt(11)
	v_add_f32_e32 v223, v73, v223
	v_cndmask_b32_e64 v70, v215, v223, s[16:17]
	ds_read_b32 v223, v243 offset:992
	s_waitcnt lgkmcnt(11)
; __device__ __forceinline__ void attn_phase(const Params& p, const bf16_t* qk, const bf16_t* vT, bf16_t* ob, char* smem) {
;     ...
; #pragma unroll
;                 for (int i = 0; i < 8; ++i)
; #pragma unroll
;                     for (int ts = 0; ts < 2; ++ts)
; #pragma unroll
;                         for (int j = 0; j < 4; ++j) {
;                             const int kc = cst + fq * 8 + ts * 4 + j;
;                             const bool valid = (kc >= cs) && (kc < cs + 16);
;                             const int ci = min(max(kc - cq + 15, 0), 30);
;                             const float bias = sbh[i * 31 + ci];
;                             s[i * 2 + ts][j] = valid ? s[i * 2 + ts][j] + bias : NEG;
;                         }
	v_add_f32_e32 v224, v66, v224
	v_cndmask_b32_e64 v73, v215, v224, s[40:41]
	ds_read_b32 v224, v236 offset:1116
	s_waitcnt lgkmcnt(11)
	v_add_f32_e32 v225, v67, v225
	v_cndmask_b32_e64 v72, v215, v225, s[62:63]
	ds_read_b32 v225, v237 offset:1116
	s_waitcnt lgkmcnt(11)
	v_add_f32_e32 v226, v68, v226
	v_cndmask_b32_e64 v67, v215, v226, s[64:65]
	ds_read_b32 v226, v238 offset:1116
	s_waitcnt lgkmcnt(11)
	v_add_f32_e32 v227, v69, v227
	v_cndmask_b32_e64 v66, v215, v227, s[66:67]
	ds_read_b32 v227, v239 offset:1116
	s_waitcnt lgkmcnt(11)
	v_add_f32_e32 v228, v62, v228
	v_cndmask_b32_e64 v69, v215, v228, s[10:11]
	ds_read_b32 v228, v240 offset:1116
	s_waitcnt lgkmcnt(11)
	v_add_f32_e32 v229, v63, v229
	v_cndmask_b32_e64 v68, v215, v229, s[12:13]
	ds_read_b32 v229, v241 offset:1116
	s_waitcnt lgkmcnt(11)
	v_add_f32_e32 v230, v64, v230
	v_cndmask_b32_e64 v63, v215, v230, s[14:15]
	ds_read_b32 v230, v242 offset:1116
	s_waitcnt lgkmcnt(11)
	v_add_f32_e32 v231, v65, v231
	v_cndmask_b32_e64 v62, v215, v231, s[16:17]
	ds_read_b32 v231, v243 offset:1116
	s_waitcnt lgkmcnt(11)
	v_add_f32_e32 v220, v58, v220
	v_cndmask_b32_e64 v65, v215, v220, s[40:41]
	ds_read_b32 v220, v236 offset:1240
	s_waitcnt lgkmcnt(11)
	v_add_f32_e32 v221, v59, v221
	v_cndmask_b32_e64 v64, v215, v221, s[62:63]
	ds_read_b32 v221, v237 offset:1240
	s_waitcnt lgkmcnt(11)
	v_add_f32_e32 v222, v60, v222
	v_cndmask_b32_e64 v59, v215, v222, s[64:65]
	ds_read_b32 v222, v238 offset:1240
	s_waitcnt lgkmcnt(11)
	v_add_f32_e32 v223, v61, v223
	v_cndmask_b32_e64 v58, v215, v223, s[66:67]
	ds_read_b32 v223, v239 offset:1240
	s_waitcnt lgkmcnt(11)
	v_add_f32_e32 v224, v54, v224
	v_cndmask_b32_e64 v61, v215, v224, s[10:11]
	ds_read_b32 v224, v240 offset:1240
	s_waitcnt lgkmcnt(11)
	v_add_f32_e32 v225, v55, v225
	v_cndmask_b32_e64 v60, v215, v225, s[12:13]
	ds_read_b32 v225, v241 offset:1240
	s_waitcnt lgkmcnt(11)
	v_add_f32_e32 v226, v56, v226
	v_cndmask_b32_e64 v55, v215, v226, s[14:15]
	ds_read_b32 v226, v242 offset:1240
	s_waitcnt lgkmcnt(11)
	v_add_f32_e32 v227, v57, v227
	v_cndmask_b32_e64 v54, v215, v227, s[16:17]
	ds_read_b32 v227, v243 offset:1240
	s_waitcnt lgkmcnt(11)
	v_add_f32_e32 v228, v50, v228
	v_cndmask_b32_e64 v57, v215, v228, s[40:41]
	ds_read_b32 v228, v236 offset:1364
	s_waitcnt lgkmcnt(11)
	v_add_f32_e32 v229, v51, v229
	v_cndmask_b32_e64 v56, v215, v229, s[62:63]
	ds_read_b32 v229, v237 offset:1364
	s_waitcnt lgkmcnt(11)
	v_add_f32_e32 v230, v52, v230
	v_cndmask_b32_e64 v51, v215, v230, s[64:65]
	ds_read_b32 v230, v238 offset:1364
	s_waitcnt lgkmcnt(11)
	v_add_f32_e32 v231, v53, v231
	v_cndmask_b32_e64 v50, v215, v231, s[66:67]
	ds_read_b32 v231, v239 offset:1364
	s_waitcnt lgkmcnt(11)
	v_add_f32_e32 v220, v46, v220
	v_cndmask_b32_e64 v53, v215, v220, s[10:11]
	ds_read_b32 v220, v240 offset:1364
	s_waitcnt lgkmcnt(11)
	v_add_f32_e32 v221, v47, v221
	v_cndmask_b32_e64 v52, v215, v221, s[12:13]
	ds_read_b32 v221, v241 offset:1364
	s_waitcnt lgkmcnt(11)
	v_add_f32_e32 v222, v48, v222
	v_cndmask_b32_e64 v47, v215, v222, s[14:15]
	ds_read_b32 v222, v242 offset:1364
	s_waitcnt lgkmcnt(11)
	v_add_f32_e32 v223, v49, v223
	v_cndmask_b32_e64 v46, v215, v223, s[16:17]
	ds_read_b32 v223, v243 offset:1364
	s_waitcnt lgkmcnt(11)
	v_add_f32_e32 v224, v42, v224
	v_cndmask_b32_e64 v49, v215, v224, s[40:41]
	ds_read_b32 v224, v236 offset:1488
	s_waitcnt lgkmcnt(11)
	v_add_f32_e32 v225, v43, v225
	v_cndmask_b32_e64 v48, v215, v225, s[62:63]
	ds_read_b32 v225, v237 offset:1488
	s_waitcnt lgkmcnt(11)
	v_add_f32_e32 v226, v44, v226
	v_cndmask_b32_e64 v43, v215, v226, s[64:65]
	ds_read_b32 v226, v238 offset:1488
	s_waitcnt lgkmcnt(11)
	v_add_f32_e32 v227, v45, v227
	v_cndmask_b32_e64 v42, v215, v227, s[66:67]
	ds_read_b32 v227, v239 offset:1488
	s_waitcnt lgkmcnt(11)
	v_add_f32_e32 v228, v30, v228
	v_cndmask_b32_e64 v45, v215, v228, s[10:11]
	ds_read_b32 v228, v240 offset:1488
	s_waitcnt lgkmcnt(11)
	v_add_f32_e32 v229, v31, v229
	v_cndmask_b32_e64 v44, v215, v229, s[12:13]
	ds_read_b32 v229, v241 offset:1488
	s_waitcnt lgkmcnt(11)
	v_add_f32_e32 v230, v32, v230
	v_cndmask_b32_e64 v31, v215, v230, s[14:15]
	ds_read_b32 v230, v242 offset:1488
	s_waitcnt lgkmcnt(11)
	v_add_f32_e32 v231, v33, v231
	v_cndmask_b32_e64 v30, v215, v231, s[16:17]
	ds_read_b32 v231, v243 offset:1488
	s_waitcnt lgkmcnt(11)
	v_add_f32_e32 v220, v26, v220
	v_cndmask_b32_e64 v33, v215, v220, s[40:41]
	ds_read_b32 v220, v236 offset:1612
	s_waitcnt lgkmcnt(11)
	v_add_f32_e32 v221, v27, v221
	v_cndmask_b32_e64 v32, v215, v221, s[62:63]
	ds_read_b32 v221, v237 offset:1612
	s_waitcnt lgkmcnt(11)
	v_add_f32_e32 v222, v28, v222
	v_cndmask_b32_e64 v27, v215, v222, s[64:65]
	ds_read_b32 v222, v238 offset:1612
	s_waitcnt lgkmcnt(11)
	v_add_f32_e32 v223, v29, v223
	v_cndmask_b32_e64 v26, v215, v223, s[66:67]
	ds_read_b32 v223, v239 offset:1612
	s_waitcnt lgkmcnt(11)
	v_add_f32_e32 v224, v38, v224
	v_cndmask_b32_e64 v29, v215, v224, s[10:11]
	ds_read_b32 v224, v240 offset:1612
	s_waitcnt lgkmcnt(11)
	v_add_f32_e32 v225, v39, v225
	v_cndmask_b32_e64 v28, v215, v225, s[12:13]
	ds_read_b32 v225, v241 offset:1612
	s_waitcnt lgkmcnt(11)
	v_add_f32_e32 v226, v40, v226
	v_cndmask_b32_e64 v39, v215, v226, s[14:15]
	ds_read_b32 v226, v242 offset:1612
	s_waitcnt lgkmcnt(11)
	v_add_f32_e32 v227, v41, v227
	v_cndmask_b32_e64 v38, v215, v227, s[16:17]
	ds_read_b32 v227, v243 offset:1612
	s_waitcnt lgkmcnt(11)
	v_add_f32_e32 v228, v34, v228
	v_cndmask_b32_e64 v41, v215, v228, s[40:41]
	ds_read_b32 v228, v236 offset:1736
	s_waitcnt lgkmcnt(11)
	v_add_f32_e32 v229, v35, v229
	v_cndmask_b32_e64 v40, v215, v229, s[62:63]
	ds_read_b32 v229, v237 offset:1736
	s_waitcnt lgkmcnt(11)
; template <bool VLDS>
; __device__ __forceinline__ void attn_block(f32x4 (&s)[16], float& m, float& l, f32x4 (&o)[4], const bf16_t* vrow, int tokb, int tokstride, int fq,
;                                            LAS unsigned char* vl) {
;     float mm = -1e30f;
; #pragma unroll
;     for (int i = 0; i < 16; ++i) mm = fmaxf(mm, fmaxf(fmaxf(s[i][0], s[i][1]), fmaxf(s[i][2], s[i][3])));
;     mm = fmaxf(mm, __shfl_xor(mm, 16));
;     mm = fmaxf(mm, __shfl_xor(mm, 32));
; __device__ __forceinline__ void attn_phase(const Params& p, const bf16_t* qk, const bf16_t* vT, bf16_t* ob, char* smem) {
;     ...
; #pragma unroll
;                 for (int i = 0; i < 8; ++i)
; #pragma unroll
;                     for (int ts = 0; ts < 2; ++ts)
; #pragma unroll
;                         for (int j = 0; j < 4; ++j) {
;                             const int kc = cst + fq * 8 + ts * 4 + j;
;                             const bool valid = (kc >= cs) && (kc < cs + 16);
;                             const int ci = min(max(kc - cq + 15, 0), 30);
;                             const float bias = sbh[i * 31 + ci];
;                             s[i * 2 + ts][j] = valid ? s[i * 2 + ts][j] + bias : NEG;
;                         }
	v_add_f32_e32 v230, v36, v230
	v_cndmask_b32_e64 v84, v215, v230, s[64:65]
	ds_read_b32 v230, v238 offset:1736
	s_waitcnt lgkmcnt(11)
	v_add_f32_e32 v231, v37, v231
	v_cndmask_b32_e64 v34, v215, v231, s[66:67]
	ds_read_b32 v231, v239 offset:1736
	s_waitcnt lgkmcnt(11)
	v_add_f32_e32 v220, v22, v220
	v_cndmask_b32_e64 v102, v215, v220, s[10:11]
	ds_read_b32 v220, v240 offset:1736
	s_waitcnt lgkmcnt(11)
	v_add_f32_e32 v221, v23, v221
	v_cndmask_b32_e64 v85, v215, v221, s[12:13]
	ds_read_b32 v221, v241 offset:1736
	s_waitcnt lgkmcnt(11)
	v_add_f32_e32 v222, v24, v222
	v_cndmask_b32_e64 v113, v215, v222, s[14:15]
	ds_read_b32 v222, v242 offset:1736
	s_waitcnt lgkmcnt(11)
	v_add_f32_e32 v223, v25, v223
	v_cndmask_b32_e64 v112, v215, v223, s[16:17]
	ds_read_b32 v223, v243 offset:1736
	s_waitcnt lgkmcnt(11)
	v_add_f32_e32 v224, v18, v224
	v_cndmask_b32_e64 v25, v215, v224, s[40:41]
	s_waitcnt lgkmcnt(10)
	v_add_f32_e32 v225, v19, v225
	v_cndmask_b32_e64 v24, v215, v225, s[62:63]
	s_waitcnt lgkmcnt(9)
	v_add_f32_e32 v226, v20, v226
	v_cndmask_b32_e64 v115, v215, v226, s[64:65]
	s_waitcnt lgkmcnt(8)
	v_add_f32_e32 v227, v21, v227
	v_cndmask_b32_e64 v114, v215, v227, s[66:67]
	s_waitcnt lgkmcnt(7)
	v_add_f32_e32 v228, v14, v228
	v_cndmask_b32_e64 v21, v215, v228, s[10:11]
	s_waitcnt lgkmcnt(6)
	v_add_f32_e32 v229, v15, v229
	v_cndmask_b32_e64 v20, v215, v229, s[12:13]
	s_waitcnt lgkmcnt(5)
	v_add_f32_e32 v230, v16, v230
	v_cndmask_b32_e64 v116, v215, v230, s[14:15]
	s_waitcnt lgkmcnt(4)
	v_add_f32_e32 v231, v17, v231
	v_cndmask_b32_e64 v77, v215, v231, s[16:17]
	s_waitcnt lgkmcnt(3)
	v_add_f32_e32 v220, v10, v220
	v_cndmask_b32_e64 v79, v215, v220, s[40:41]
	s_waitcnt lgkmcnt(2)
	v_add_f32_e32 v221, v11, v221
	v_cndmask_b32_e64 v78, v215, v221, s[62:63]
	s_waitcnt lgkmcnt(1)
	v_add_f32_e32 v222, v12, v222
	v_cndmask_b32_e64 v11, v215, v222, s[64:65]
	s_waitcnt lgkmcnt(0)
	v_add_f32_e32 v223, v13, v223
	v_cndmask_b32_e64 v10, v215, v223, s[66:67]
	v_max_f32_e32 v12, v70, v70
	v_max_f32_e32 v13, v71, v71
	v_max_f32_e32 v12, v13, v12
	v_max_f32_e32 v13, v66, v66
	v_max_f32_e32 v14, v67, v67
	v_max_f32_e32 v13, v14, v13
	v_max3_f32 v12, v75, v74, v12
	v_max3_f32 v13, v73, v72, v13
	v_max3_f32 v12, v12, s19, v13
	v_max_f32_e32 v13, v62, v62
	v_max_f32_e32 v14, v63, v63
	v_max_f32_e32 v13, v14, v13
	v_max_f32_e32 v14, v58, v58
	v_max_f32_e32 v15, v59, v59
	v_max_f32_e32 v14, v15, v14
	v_max3_f32 v13, v69, v68, v13
	v_max3_f32 v14, v65, v64, v14
	v_max3_f32 v12, v12, v13, v14
	v_max_f32_e32 v13, v54, v54
	v_max_f32_e32 v14, v55, v55
	v_max_f32_e32 v13, v14, v13
	v_max_f32_e32 v14, v50, v50
	v_max_f32_e32 v15, v51, v51
	v_max_f32_e32 v14, v15, v14
	v_max3_f32 v13, v61, v60, v13
	v_max3_f32 v14, v57, v56, v14
	v_max3_f32 v12, v12, v13, v14
	v_max_f32_e32 v13, v46, v46
	v_max_f32_e32 v14, v47, v47
	v_max_f32_e32 v13, v14, v13
	v_max_f32_e32 v14, v42, v42
	v_max_f32_e32 v15, v43, v43
	v_max_f32_e32 v14, v15, v14
	v_max3_f32 v13, v53, v52, v13
	v_max3_f32 v14, v49, v48, v14
	v_max3_f32 v12, v12, v13, v14
	v_max_f32_e32 v13, v30, v30
	v_max_f32_e32 v14, v31, v31
	v_max_f32_e32 v13, v14, v13
	v_max_f32_e32 v14, v26, v26
	v_max_f32_e32 v15, v27, v27
	v_max_f32_e32 v14, v15, v14
	v_max3_f32 v13, v45, v44, v13
	v_max3_f32 v14, v33, v32, v14
	v_max3_f32 v12, v12, v13, v14
	v_max_f32_e32 v13, v38, v38
	v_max_f32_e32 v14, v39, v39
	v_max_f32_e32 v13, v14, v13
	v_max_f32_e32 v14, v34, v34
	v_max_f32_e32 v15, v84, v84
	v_max_f32_e32 v14, v15, v14
	v_max3_f32 v13, v29, v28, v13
	v_max3_f32 v14, v41, v40, v14
	v_max3_f32 v12, v12, v13, v14
	v_max_f32_e32 v13, v112, v112
	v_max_f32_e32 v14, v113, v113
	v_max_f32_e32 v13, v14, v13
	v_max_f32_e32 v14, v114, v114
	v_max_f32_e32 v15, v115, v115
	v_max_f32_e32 v14, v15, v14
	v_max3_f32 v13, v102, v85, v13
	v_max3_f32 v14, v25, v24, v14
	v_max3_f32 v12, v12, v13, v14
	v_max_f32_e32 v13, v77, v77
	v_max_f32_e32 v14, v116, v116
	v_max_f32_e32 v13, v14, v13
	v_max_f32_e32 v14, v10, v10
	v_max_f32_e32 v15, v11, v11
	v_max_f32_e32 v14, v15, v14
	v_max3_f32 v13, v21, v20, v13
	v_max3_f32 v14, v79, v78, v14
	v_max3_f32 v12, v12, v13, v14
	ds_bpermute_b32 v13, v110, v12
	s_or_b32 s0, s4, s78
	s_or_b32 s10, s0, s7
	s_ashr_i32 s11, s10, 31
	s_mov_b32 s0, 0x110000
	s_waitcnt lgkmcnt(0)
	v_max_f32_e32 v13, v13, v13
	v_max_f32_e32 v12, v12, v13
	ds_bpermute_b32 v13, v111, v12
	s_waitcnt lgkmcnt(0)
; __device__ __forceinline__ float fexp(float x) { return __builtin_amdgcn_exp2f(x * 1.4426950408889634f); }
; template <bool VLDS>
; __device__ __forceinline__ void attn_block(f32x4 (&s)[16], float& m, float& l, f32x4 (&o)[4], const bf16_t* vrow, int tokb, int tokstride, int fq,
;                                            LAS unsigned char* vl) {
;     ...
;     float sum = 0.f;
; #pragma unroll
;     for (int i = 0; i < 16; ++i)
; #pragma unroll
;         for (int j = 0; j < 4; ++j) { const float e = fexp(s[i][j] - mm); s[i][j] = e; sum += e; }
;     sum += __shfl_xor(sum, 16);
;     sum += __shfl_xor(sum, 32);
	v_max_f32_e32 v13, v13, v13
	v_max_f32_e32 v103, v12, v13
	v_sub_f32_e32 v13, v74, v103
	v_mul_f32_e32 v13, 0x3fb8aa3b, v13
	v_exp_f32_e32 v15, v13
	v_sub_f32_e32 v13, v71, v103
	v_mul_f32_e32 v13, 0x3fb8aa3b, v13
	v_exp_f32_e32 v18, v13
	v_sub_f32_e32 v13, v70, v103
	v_mul_f32_e32 v13, 0x3fb8aa3b, v13
	v_exp_f32_e32 v19, v13
	v_sub_f32_e32 v13, v73, v103
	v_mul_f32_e32 v13, 0x3fb8aa3b, v13
	v_exp_f32_e32 v22, v13
	v_sub_f32_e32 v13, v72, v103
	v_mul_f32_e32 v13, 0x3fb8aa3b, v13
	v_exp_f32_e32 v23, v13
	v_sub_f32_e32 v13, v67, v103
	v_mul_f32_e32 v13, 0x3fb8aa3b, v13
	v_exp_f32_e32 v71, v13
	v_sub_f32_e32 v13, v66, v103
	v_mul_f32_e32 v13, 0x3fb8aa3b, v13
	v_exp_f32_e32 v74, v13
	v_sub_f32_e32 v13, v69, v103
	v_mul_f32_e32 v13, 0x3fb8aa3b, v13
	v_exp_f32_e32 v66, v13
	v_sub_f32_e32 v13, v68, v103
	v_mul_f32_e32 v13, 0x3fb8aa3b, v13
	v_exp_f32_e32 v67, v13
	v_sub_f32_e32 v13, v63, v103
	v_mul_f32_e32 v13, 0x3fb8aa3b, v13
	v_exp_f32_e32 v68, v13
	v_sub_f32_e32 v13, v62, v103
	v_mul_f32_e32 v13, 0x3fb8aa3b, v13
	v_exp_f32_e32 v69, v13
	v_sub_f32_e32 v13, v65, v103
	v_mul_f32_e32 v13, 0x3fb8aa3b, v13
	v_exp_f32_e32 v70, v13
	v_sub_f32_e32 v13, v64, v103
	v_mul_f32_e32 v13, 0x3fb8aa3b, v13
	v_exp_f32_e32 v73, v13
	v_sub_f32_e32 v13, v59, v103
	v_mul_f32_e32 v13, 0x3fb8aa3b, v13
	v_sub_f32_e32 v12, v75, v103
	v_exp_f32_e32 v75, v13
	v_sub_f32_e32 v13, v58, v103
	v_mul_f32_e32 v13, 0x3fb8aa3b, v13
	v_exp_f32_e32 v76, v13
	v_sub_f32_e32 v13, v61, v103
	v_mul_f32_e32 v13, 0x3fb8aa3b, v13
	v_exp_f32_e32 v58, v13
	v_sub_f32_e32 v13, v60, v103
	v_mul_f32_e32 v13, 0x3fb8aa3b, v13
	v_exp_f32_e32 v59, v13
	v_sub_f32_e32 v13, v55, v103
	v_mul_f32_e32 v13, 0x3fb8aa3b, v13
	v_exp_f32_e32 v60, v13
	v_sub_f32_e32 v13, v54, v103
	v_mul_f32_e32 v13, 0x3fb8aa3b, v13
	v_exp_f32_e32 v61, v13
	v_sub_f32_e32 v13, v57, v103
	v_mul_f32_e32 v13, 0x3fb8aa3b, v13
	v_exp_f32_e32 v62, v13
	v_sub_f32_e32 v13, v56, v103
	v_mul_f32_e32 v13, 0x3fb8aa3b, v13
	v_exp_f32_e32 v64, v13
	v_sub_f32_e32 v13, v51, v103
	v_mul_f32_e32 v13, 0x3fb8aa3b, v13
	v_exp_f32_e32 v65, v13
	v_sub_f32_e32 v13, v50, v103
	v_mul_f32_e32 v13, 0x3fb8aa3b, v13
	v_exp_f32_e32 v72, v13
	v_sub_f32_e32 v13, v53, v103
	v_mul_f32_e32 v13, 0x3fb8aa3b, v13
	v_exp_f32_e32 v50, v13
	v_sub_f32_e32 v13, v52, v103
	v_mul_f32_e32 v13, 0x3fb8aa3b, v13
	v_exp_f32_e32 v51, v13
	v_sub_f32_e32 v13, v47, v103
	v_mul_f32_e32 v13, 0x3fb8aa3b, v13
	v_exp_f32_e32 v53, v13
	v_sub_f32_e32 v13, v46, v103
	v_mul_f32_e32 v13, 0x3fb8aa3b, v13
	v_mul_f32_e32 v12, 0x3fb8aa3b, v12
	v_exp_f32_e32 v54, v13
	v_sub_f32_e32 v13, v49, v103
	v_exp_f32_e32 v14, v12
	v_mul_f32_e32 v13, 0x3fb8aa3b, v13
	v_exp_f32_e32 v55, v13
	v_sub_f32_e32 v13, v48, v103
	v_mul_f32_e32 v13, 0x3fb8aa3b, v13
	v_exp_f32_e32 v56, v13
	v_sub_f32_e32 v13, v43, v103
	v_add_f32_e32 v12, 0, v14
	v_mul_f32_e32 v13, 0x3fb8aa3b, v13
	v_add_f32_e32 v12, v15, v12
	v_exp_f32_e32 v57, v13
	v_sub_f32_e32 v13, v42, v103
	v_add_f32_e32 v12, v18, v12
	v_mul_f32_e32 v13, 0x3fb8aa3b, v13
	v_add_f32_e32 v12, v19, v12
	v_exp_f32_e32 v63, v13
	v_sub_f32_e32 v13, v45, v103
	v_add_f32_e32 v12, v22, v12
	v_mul_f32_e32 v13, 0x3fb8aa3b, v13
	v_add_f32_e32 v12, v23, v12
	v_exp_f32_e32 v43, v13
	v_sub_f32_e32 v13, v44, v103
	v_add_f32_e32 v12, v71, v12
	v_mul_f32_e32 v13, 0x3fb8aa3b, v13
	v_add_f32_e32 v12, v74, v12
	v_exp_f32_e32 v44, v13
	v_sub_f32_e32 v13, v31, v103
	v_add_f32_e32 v12, v66, v12
	v_mul_f32_e32 v13, 0x3fb8aa3b, v13
	v_add_f32_e32 v12, v67, v12
	v_exp_f32_e32 v45, v13
	v_sub_f32_e32 v13, v30, v103
	v_add_f32_e32 v12, v68, v12
	v_mul_f32_e32 v13, 0x3fb8aa3b, v13
	v_add_f32_e32 v12, v69, v12
	v_exp_f32_e32 v46, v13
	v_sub_f32_e32 v13, v33, v103
	v_add_f32_e32 v12, v70, v12
	v_mul_f32_e32 v13, 0x3fb8aa3b, v13
	v_add_f32_e32 v12, v73, v12
	v_exp_f32_e32 v47, v13
	v_sub_f32_e32 v13, v32, v103
	v_add_f32_e32 v12, v75, v12
	v_mul_f32_e32 v13, 0x3fb8aa3b, v13
	v_add_f32_e32 v12, v76, v12
	v_exp_f32_e32 v48, v13
	v_sub_f32_e32 v13, v27, v103
	v_add_f32_e32 v12, v58, v12
	v_mul_f32_e32 v13, 0x3fb8aa3b, v13
	v_add_f32_e32 v12, v59, v12
	v_exp_f32_e32 v49, v13
	v_sub_f32_e32 v13, v26, v103
	v_add_f32_e32 v12, v60, v12
	v_mul_f32_e32 v13, 0x3fb8aa3b, v13
	v_add_f32_e32 v12, v61, v12
	v_exp_f32_e32 v52, v13
	v_sub_f32_e32 v13, v29, v103
	v_add_f32_e32 v12, v62, v12
	v_mul_f32_e32 v13, 0x3fb8aa3b, v13
	v_add_f32_e32 v12, v64, v12
	v_exp_f32_e32 v35, v13
	v_sub_f32_e32 v13, v28, v103
	v_add_f32_e32 v12, v65, v12
	v_mul_f32_e32 v13, 0x3fb8aa3b, v13
	v_add_f32_e32 v12, v72, v12
	v_exp_f32_e32 v36, v13
	v_sub_f32_e32 v13, v39, v103
	v_add_f32_e32 v12, v50, v12
	v_mul_f32_e32 v13, 0x3fb8aa3b, v13
	v_add_f32_e32 v12, v51, v12
	v_exp_f32_e32 v37, v13
	v_sub_f32_e32 v13, v38, v103
	v_add_f32_e32 v12, v53, v12
	v_mul_f32_e32 v13, 0x3fb8aa3b, v13
	v_add_f32_e32 v12, v54, v12
	v_exp_f32_e32 v38, v13
	v_sub_f32_e32 v13, v41, v103
	v_add_f32_e32 v12, v55, v12
	v_mul_f32_e32 v13, 0x3fb8aa3b, v13
	v_add_f32_e32 v12, v56, v12
	v_exp_f32_e32 v39, v13
	v_sub_f32_e32 v13, v40, v103
	v_add_f32_e32 v12, v57, v12
	v_mul_f32_e32 v13, 0x3fb8aa3b, v13
	v_add_f32_e32 v12, v63, v12
	v_exp_f32_e32 v40, v13
	v_sub_f32_e32 v13, v84, v103
	v_add_f32_e32 v12, v43, v12
	v_mul_f32_e32 v13, 0x3fb8aa3b, v13
	v_add_f32_e32 v12, v44, v12
	v_exp_f32_e32 v41, v13
	v_sub_f32_e32 v13, v34, v103
	v_add_f32_e32 v12, v45, v12
	v_mul_f32_e32 v13, 0x3fb8aa3b, v13
	v_add_f32_e32 v12, v46, v12
	v_exp_f32_e32 v42, v13
	v_sub_f32_e32 v13, v102, v103
	v_add_f32_e32 v12, v47, v12
	v_mul_f32_e32 v13, 0x3fb8aa3b, v13
	v_add_f32_e32 v12, v48, v12
	v_exp_f32_e32 v27, v13
	v_sub_f32_e32 v13, v85, v103
	v_add_f32_e32 v12, v49, v12
; __device__ __forceinline__ float fexp(float x) { return __builtin_amdgcn_exp2f(x * 1.4426950408889634f); }
; #define LAS __attribute__((address_space(3)))
; template <bool VLDS>
; __device__ __forceinline__ void attn_block(f32x4 (&s)[16], float& m, float& l, f32x4 (&o)[4], const bf16_t* vrow, int tokb, int tokstride, int fq,
;                                            LAS unsigned char* vl) {
;     ...
;         for (int j = 0; j < 4; ++j) { const float e = fexp(s[i][j] - mm); s[i][j] = e; sum += e; }
;     sum += __shfl_xor(sum, 16);
;     sum += __shfl_xor(sum, 32);
; #pragma unroll
;     for (int dt = 0; dt < 4; ++dt) o[dt] = (f32x4){0.f, 0.f, 0.f, 0.f};
; #pragma unroll
;     for (int grp = 0; grp < 8; ++grp) {
;         const bf16x8 pf = mk8(pack2(s[2 * grp][0], s[2 * grp][1]), pack2(s[2 * grp][2], s[2 * grp][3]),
;                               pack2(s[2 * grp + 1][0], s[2 * grp + 1][1]), pack2(s[2 * grp + 1][2], s[2 * grp + 1][3]));
;         if (VLDS) {
; #pragma unroll
;             for (int dt = 0; dt < 4; ++dt) o[dt] = mfma16(*(const LAS bf16x8*)(vl + (grp * 4) * 1040 + dt * 256), pf, o[dt]);
;             __builtin_amdgcn_sched_barrier(0);
;         } else {
;             const bf16_t* vp = vrow + tokb + grp * tokstride + fq * 8;
; #pragma unroll
;             for (int dt = 0; dt < 4; ++dt) o[dt] = mfma16(ld8(vp + (size_t)dt * 16 * T_ALL), pf, o[dt]);
;         }
;     }
	v_mul_f32_e32 v13, 0x3fb8aa3b, v13
	v_add_f32_e32 v12, v52, v12
	v_exp_f32_e32 v28, v13
	v_sub_f32_e32 v13, v113, v103
	v_add_f32_e32 v12, v35, v12
	v_mul_f32_e32 v13, 0x3fb8aa3b, v13
	v_add_f32_e32 v12, v36, v12
	v_exp_f32_e32 v29, v13
	v_sub_f32_e32 v13, v112, v103
	v_add_f32_e32 v12, v37, v12
	v_mul_f32_e32 v13, 0x3fb8aa3b, v13
	v_add_f32_e32 v12, v38, v12
	v_exp_f32_e32 v30, v13
	v_sub_f32_e32 v13, v25, v103
	v_add_f32_e32 v12, v39, v12
	v_mul_f32_e32 v13, 0x3fb8aa3b, v13
	v_add_f32_e32 v12, v40, v12
	v_exp_f32_e32 v31, v13
	v_sub_f32_e32 v13, v24, v103
	v_add_f32_e32 v12, v41, v12
	v_mul_f32_e32 v13, 0x3fb8aa3b, v13
	v_add_f32_e32 v12, v42, v12
	v_exp_f32_e32 v32, v13
	v_sub_f32_e32 v13, v115, v103
	v_add_f32_e32 v12, v27, v12
	v_mul_f32_e32 v13, 0x3fb8aa3b, v13
	v_add_f32_e32 v12, v28, v12
	v_exp_f32_e32 v33, v13
	v_sub_f32_e32 v13, v114, v103
	v_add_f32_e32 v12, v29, v12
	v_mul_f32_e32 v13, 0x3fb8aa3b, v13
	v_add_f32_e32 v12, v30, v12
	v_exp_f32_e32 v34, v13
	v_add_f32_e32 v12, v31, v12
	v_add_f32_e32 v12, v32, v12
	v_add_f32_e32 v12, v33, v12
	v_add_f32_e32 v13, v34, v12
	v_sub_f32_e32 v12, v21, v103
	v_mul_f32_e32 v12, 0x3fb8aa3b, v12
	v_exp_f32_e32 v12, v12
	v_sub_f32_e32 v11, v11, v103
	v_mul_f32_e32 v11, 0x3fb8aa3b, v11
	v_sub_f32_e32 v10, v10, v103
	v_add_f32_e32 v16, v12, v13
	v_sub_f32_e32 v13, v20, v103
	v_mul_f32_e32 v13, 0x3fb8aa3b, v13
	v_exp_f32_e32 v13, v13
	v_mul_f32_e32 v10, 0x3fb8aa3b, v10
	v_cvt_pk_bf16_f32 v81, v71, v74
	v_cvt_pk_bf16_f32 v66, v66, v67
	v_add_f32_e32 v17, v13, v16
	v_sub_f32_e32 v16, v116, v103
	v_mul_f32_e32 v16, 0x3fb8aa3b, v16
	v_exp_f32_e32 v16, v16
	v_cvt_pk_bf16_f32 v67, v68, v69
	v_cvt_pk_bf16_f32 v69, v75, v76
	v_cvt_pk_bf16_f32 v80, v22, v23
	v_add_f32_e32 v20, v16, v17
	v_sub_f32_e32 v17, v77, v103
	v_mul_f32_e32 v17, 0x3fb8aa3b, v17
	v_exp_f32_e32 v17, v17
	v_cvt_pk_bf16_f32 v68, v70, v73
	v_cvt_pk_bf16_f32 v58, v58, v59
	v_cvt_pk_bf16_f32 v59, v60, v61
	v_add_f32_e32 v21, v17, v20
	v_sub_f32_e32 v20, v79, v103
	v_mul_f32_e32 v20, 0x3fb8aa3b, v20
	v_exp_f32_e32 v20, v20
	v_cvt_pk_bf16_f32 v79, v18, v19
	v_cvt_pk_bf16_f32 v61, v65, v72
	v_cvt_pk_bf16_f32 v36, v35, v36
	v_add_f32_e32 v24, v20, v21
	v_sub_f32_e32 v21, v78, v103
	v_mul_f32_e32 v21, 0x3fb8aa3b, v21
	v_exp_f32_e32 v21, v21
	v_cvt_pk_bf16_f32 v78, v14, v15
	v_cvt_pk_bf16_f32 v29, v29, v30
	v_cvt_pk_bf16_f32 v30, v31, v32
	v_add_f32_e32 v25, v21, v24
	v_exp_f32_e32 v24, v11
	v_cvt_pk_bf16_f32 v31, v33, v34
	v_cvt_pk_bf16_f32 v60, v62, v64
	v_cvt_pk_bf16_f32 v64, v50, v51
	v_add_f32_e32 v11, v24, v25
	v_exp_f32_e32 v25, v10
	v_cvt_pk_bf16_f32 v45, v45, v46
	v_cvt_pk_bf16_f32 v46, v47, v48
	v_cvt_pk_bf16_f32 v47, v49, v52
	v_add_f32_e32 v10, v25, v11
	ds_bpermute_b32 v11, v110, v10
	v_cvt_pk_bf16_f32 v65, v53, v54
	v_cvt_pk_bf16_f32 v44, v43, v44
	v_cvt_pk_bf16_f32 v37, v37, v38
	v_cvt_pk_bf16_f32 v38, v39, v40
	s_waitcnt lgkmcnt(0)
	v_add_f32_e32 v26, v10, v11
	v_lshl_add_u64 v[10:11], s[10:11], 1, v[96:97]
	global_load_dwordx4 v[82:85], v[10:11], off
	global_load_dwordx4 v[74:77], v[10:11], off offset:128
	v_add_co_u32_e32 v14, vcc, s0, v10
	s_waitcnt vmcnt(1)
	v_mfma_f32_16x16x32_bf16 v[82:85], v[82:85], v[78:81], 0
	v_addc_co_u32_e32 v15, vcc, 0, v11, vcc
	global_load_dwordx4 v[112:115], v[14:15], off
	global_load_dwordx4 v[32:35], v[10:11], off offset:768
	s_waitcnt vmcnt(2)
	v_mfma_f32_16x16x32_bf16 v[74:77], v[74:77], v[66:69], v[82:85]
	global_load_dwordx4 v[70:73], v[10:11], off offset:256
	global_load_dwordx4 v[48:51], v[10:11], off offset:512
	s_mov_b32 s0, 0x220000
	global_load_dwordx4 v[82:85], v[14:15], off offset:128
	v_add_co_u32_e32 v18, vcc, s0, v10
	s_waitcnt vmcnt(4)
	v_mfma_f32_16x16x32_bf16 v[112:115], v[112:115], v[78:81], 0
	v_addc_co_u32_e32 v19, vcc, 0, v11, vcc
	global_load_dwordx4 v[116:119], v[18:19], off
	s_waitcnt vmcnt(3)
	v_mfma_f32_16x16x32_bf16 v[70:73], v[70:73], v[58:61], v[74:77]
	s_mov_b32 s0, 0x330000
	v_add_co_u32_e32 v22, vcc, s0, v10
	s_nop 0
	global_load_dwordx4 v[74:77], v[14:15], off offset:256
	s_waitcnt vmcnt(2)
; #define LAS __attribute__((address_space(3)))
; template <bool VLDS>
; __device__ __forceinline__ void attn_block(f32x4 (&s)[16], float& m, float& l, f32x4 (&o)[4], const bf16_t* vrow, int tokb, int tokstride, int fq,
;                                            LAS unsigned char* vl) {
;     ...
;     for (int grp = 0; grp < 8; ++grp) {
;         const bf16x8 pf = mk8(pack2(s[2 * grp][0], s[2 * grp][1]), pack2(s[2 * grp][2], s[2 * grp][3]),
;                               pack2(s[2 * grp + 1][0], s[2 * grp + 1][1]), pack2(s[2 * grp + 1][2], s[2 * grp + 1][3]));
;         if (VLDS) {
; #pragma unroll
;             for (int dt = 0; dt < 4; ++dt) o[dt] = mfma16(*(const LAS bf16x8*)(vl + (grp * 4) * 1040 + dt * 256), pf, o[dt]);
;             __builtin_amdgcn_sched_barrier(0);
;         } else {
;             const bf16_t* vp = vrow + tokb + grp * tokstride + fq * 8;
; #pragma unroll
;             for (int dt = 0; dt < 4; ++dt) o[dt] = mfma16(ld8(vp + (size_t)dt * 16 * T_ALL), pf, o[dt]);
;         }
;     }
	v_mfma_f32_16x16x32_bf16 v[82:85], v[82:85], v[66:69], v[112:115]
	v_addc_co_u32_e32 v23, vcc, 0, v11, vcc
	global_load_dwordx4 v[120:123], v[22:23], off
	s_nop 0
	global_load_dwordx4 v[112:115], v[18:19], off offset:128
	s_waitcnt vmcnt(3)
	v_mfma_f32_16x16x32_bf16 v[116:119], v[116:119], v[78:81], 0
	v_cvt_pk_bf16_f32 v39, v41, v42
	v_cvt_pk_bf16_f32 v28, v27, v28
	ds_bpermute_b32 v27, v111, v26
	s_waitcnt vmcnt(0)
	v_mfma_f32_16x16x32_bf16 v[112:115], v[112:115], v[66:69], v[116:119]
	s_nop 2
	global_load_dwordx4 v[116:119], v[22:23], off offset:128
	global_load_dwordx4 v[40:43], v[10:11], off offset:640
	s_waitcnt lgkmcnt(0)
	v_add_f32_e32 v102, v26, v27
	v_mfma_f32_16x16x32_bf16 v[78:81], v[120:123], v[78:81], 0
	s_waitcnt vmcnt(1)
	v_mfma_f32_16x16x32_bf16 v[66:69], v[116:119], v[66:69], v[78:81]
	s_nop 5
	global_load_dwordx4 v[78:81], v[18:19], off offset:256
	v_mfma_f32_16x16x32_bf16 v[74:77], v[74:77], v[58:61], v[82:85]
	s_nop 2
	global_load_dwordx4 v[82:85], v[22:23], off offset:256
	s_waitcnt vmcnt(1)
	v_mfma_f32_16x16x32_bf16 v[78:81], v[78:81], v[58:61], v[112:115]
	s_waitcnt vmcnt(0)
	v_mfma_f32_16x16x32_bf16 v[58:61], v[82:85], v[58:61], v[66:69]
	s_nop 2
	v_cvt_pk_bf16_f32 v66, v55, v56
	v_cvt_pk_bf16_f32 v67, v57, v63
	global_load_dwordx4 v[54:57], v[10:11], off offset:384
	s_waitcnt vmcnt(0)
	v_mfma_f32_16x16x32_bf16 v[54:57], v[54:57], v[64:67], v[70:73]
	s_nop 2
	global_load_dwordx4 v[68:71], v[14:15], off offset:384
	v_mfma_f32_16x16x32_bf16 v[48:51], v[48:51], v[44:47], v[54:57]
	s_nop 2
	global_load_dwordx4 v[52:55], v[14:15], off offset:512
	s_waitcnt vmcnt(1)
	v_mfma_f32_16x16x32_bf16 v[68:71], v[68:71], v[64:67], v[74:77]
	s_nop 2
	global_load_dwordx4 v[72:75], v[18:19], off offset:384
	v_mfma_f32_16x16x32_bf16 v[40:43], v[40:43], v[36:39], v[48:51]
	s_nop 2
	global_load_dwordx4 v[48:51], v[14:15], off offset:640
	s_waitcnt vmcnt(2)
	v_mfma_f32_16x16x32_bf16 v[52:55], v[52:55], v[44:47], v[68:71]
	v_mfma_f32_16x16x32_bf16 v[32:35], v[32:35], v[28:31], v[40:43]
	s_nop 2
	global_load_dwordx4 v[40:43], v[14:15], off offset:768
	s_waitcnt vmcnt(1)
	v_mfma_f32_16x16x32_bf16 v[48:51], v[48:51], v[36:39], v[52:55]
	s_nop 2
	global_load_dwordx4 v[52:55], v[18:19], off offset:640
	v_mfma_f32_16x16x32_bf16 v[72:75], v[72:75], v[64:67], v[78:81]
	s_nop 2
	global_load_dwordx4 v[76:79], v[22:23], off offset:384
	s_waitcnt vmcnt(0)
	v_mfma_f32_16x16x32_bf16 v[58:61], v[76:79], v[64:67], v[58:61]
	global_load_dwordx4 v[62:65], v[18:19], off offset:512
	global_load_dwordx4 v[66:69], v[22:23], off offset:512
	s_waitcnt vmcnt(1)
	v_mfma_f32_16x16x32_bf16 v[62:65], v[62:65], v[44:47], v[72:75]
	s_waitcnt vmcnt(0)
	v_mfma_f32_16x16x32_bf16 v[44:47], v[66:69], v[44:47], v[58:61]
	s_nop 2
	global_load_dwordx4 v[56:59], v[22:23], off offset:640
	v_mfma_f32_16x16x32_bf16 v[52:55], v[52:55], v[36:39], v[62:65]
	s_waitcnt vmcnt(0)
	v_mfma_f32_16x16x32_bf16 v[36:39], v[56:59], v[36:39], v[44:47]
	s_nop 2
	global_load_dwordx4 v[44:47], v[18:19], off offset:768
	v_mfma_f32_16x16x32_bf16 v[40:43], v[40:43], v[28:31], v[48:51]
	s_nop 2
	global_load_dwordx4 v[48:51], v[22:23], off offset:768
	s_waitcnt vmcnt(1)
	v_mfma_f32_16x16x32_bf16 v[44:47], v[44:47], v[28:31], v[52:55]
	s_waitcnt vmcnt(0)
	v_mfma_f32_16x16x32_bf16 v[28:31], v[48:51], v[28:31], v[36:39]
	s_nop 2
	v_cvt_pk_bf16_f32 v36, v12, v13
	v_cvt_pk_bf16_f32 v37, v16, v17
	v_cvt_pk_bf16_f32 v38, v20, v21
	v_cvt_pk_bf16_f32 v39, v24, v25
	global_load_dwordx4 v[10:13], v[10:11], off offset:896
	s_nop 0
	global_load_dwordx4 v[14:17], v[14:15], off offset:896
	s_waitcnt vmcnt(1)
	v_mfma_f32_16x16x32_bf16 v[10:13], v[10:13], v[36:39], v[32:35]
	global_load_dwordx4 v[18:21], v[18:19], off offset:896
	s_nop 0
	global_load_dwordx4 v[22:25], v[22:23], off offset:896
	s_waitcnt vmcnt(2)
	v_mfma_f32_16x16x32_bf16 v[14:17], v[14:17], v[36:39], v[40:43]
	s_waitcnt vmcnt(1)
	v_mfma_f32_16x16x32_bf16 v[18:21], v[18:21], v[36:39], v[44:47]
	s_waitcnt vmcnt(0)
	v_mfma_f32_16x16x32_bf16 v[22:25], v[22:25], v[36:39], v[28:31]
	s_branch .LBB0_257
